# cross-tile prefetch: first K iteration peeled so that the stage-1 wait also tolerates the previous epilogue's un-acked stores
# baseline (speedup 1.0000x reference)
.Lg1_first:
	s_barrier
	ds_read_b128 v[64:67], v120 offset:0
	ds_read_b128 v[72:75], v124 offset:0
	ds_read_b128 v[76:79], v124 offset:4096
	ds_read_b128 v[68:71], v120 offset:4096
	ds_read_b128 v[80:83], v121 offset:0
	ds_read_b128 v[88:91], v125 offset:0
	ds_read_b128 v[92:95], v125 offset:4096
	ds_read_b128 v[84:87], v121 offset:4096
	s_waitcnt lgkmcnt(4)
	v_mfma_f32_32x32x16_bf16 v[48:63], v[64:67], v[72:75], v[48:63]
	ds_read_b128 v[96:99], v122 offset:0
	v_mfma_f32_32x32x16_bf16 v[16:31], v[64:67], v[76:79], v[16:31]
	ds_read_b128 v[104:107], v126 offset:0
	v_mfma_f32_32x32x16_bf16 v[32:47], v[68:71], v[72:75], v[32:47]
	ds_read_b128 v[108:111], v126 offset:4096
	v_mfma_f32_32x32x16_bf16 v[0:15], v[68:71], v[76:79], v[0:15]
	ds_read_b128 v[100:103], v122 offset:4096
	s_waitcnt lgkmcnt(4)
	v_mfma_f32_32x32x16_bf16 v[48:63], v[80:83], v[88:91], v[48:63]
	ds_read_b128 v[64:67], v123 offset:0
	v_mfma_f32_32x32x16_bf16 v[16:31], v[80:83], v[92:95], v[16:31]
	ds_read_b128 v[72:75], v127 offset:0
	v_mfma_f32_32x32x16_bf16 v[32:47], v[84:87], v[88:91], v[32:47]
	ds_read_b128 v[76:79], v127 offset:4096
	v_mfma_f32_32x32x16_bf16 v[0:15], v[84:87], v[92:95], v[0:15]
	ds_read_b128 v[68:71], v123 offset:4096
	s_waitcnt lgkmcnt(4)
	v_mfma_f32_32x32x16_bf16 v[48:63], v[96:99], v[104:107], v[48:63]
	v_mfma_f32_32x32x16_bf16 v[16:31], v[96:99], v[108:111], v[16:31]
	v_mfma_f32_32x32x16_bf16 v[32:47], v[100:103], v[104:107], v[32:47]
	v_mfma_f32_32x32x16_bf16 v[0:15], v[100:103], v[108:111], v[0:15]
	s_waitcnt lgkmcnt(0)
	v_mfma_f32_32x32x16_bf16 v[48:63], v[64:67], v[72:75], v[48:63]
	v_mfma_f32_32x32x16_bf16 v[16:31], v[64:67], v[76:79], v[16:31]
	v_mfma_f32_32x32x16_bf16 v[32:47], v[68:71], v[72:75], v[32:47]
	v_mfma_f32_32x32x16_bf16 v[0:15], v[68:71], v[76:79], v[0:15]
	s_barrier
	s_add_u32 m0, s98, 0x0
	s_nop 0
	global_load_lds_dwordx4 v112, s[0:1] offset:0
	global_load_lds_dwordx4 v113, s[0:1] offset:1024
	global_load_lds_dwordx4 v114, s[0:1] offset:2048
	global_load_lds_dwordx4 v115, s[0:1] offset:3072
	s_add_u32 m0, s98, 0x1000
	s_nop 0
	global_load_lds_dwordx4 v116, s[0:1] offset:0
	global_load_lds_dwordx4 v117, s[0:1] offset:1024
	global_load_lds_dwordx4 v118, s[0:1] offset:2048
	global_load_lds_dwordx4 v119, s[0:1] offset:3072
	s_add_u32 s0, s0, 0x80
	s_addc_u32 s1, s1, 0
	s_cmp_lg_u32 s101, 0
	s_cbranch_scc1 .Lg1_w1p
	s_waitcnt vmcnt(8)
	s_branch .Lg1_s1

.Lg1_s1:
	s_barrier
	ds_read_b128 v[64:67], v120 offset:32768
	ds_read_b128 v[72:75], v124 offset:32768
	ds_read_b128 v[76:79], v124 offset:36864
	ds_read_b128 v[68:71], v120 offset:36864
	ds_read_b128 v[80:83], v121 offset:32768
	ds_read_b128 v[88:91], v125 offset:32768
	ds_read_b128 v[92:95], v125 offset:36864
	ds_read_b128 v[84:87], v121 offset:36864
	s_waitcnt lgkmcnt(4)
	v_mfma_f32_32x32x16_bf16 v[48:63], v[64:67], v[72:75], v[48:63]
	ds_read_b128 v[96:99], v122 offset:32768
	v_mfma_f32_32x32x16_bf16 v[16:31], v[64:67], v[76:79], v[16:31]
	ds_read_b128 v[104:107], v126 offset:32768
	v_mfma_f32_32x32x16_bf16 v[32:47], v[68:71], v[72:75], v[32:47]
	ds_read_b128 v[108:111], v126 offset:36864
	v_mfma_f32_32x32x16_bf16 v[0:15], v[68:71], v[76:79], v[0:15]
	ds_read_b128 v[100:103], v122 offset:36864
	s_waitcnt lgkmcnt(4)
	v_mfma_f32_32x32x16_bf16 v[48:63], v[80:83], v[88:91], v[48:63]
	ds_read_b128 v[64:67], v123 offset:32768
	v_mfma_f32_32x32x16_bf16 v[16:31], v[80:83], v[92:95], v[16:31]
	ds_read_b128 v[72:75], v127 offset:32768
	v_mfma_f32_32x32x16_bf16 v[32:47], v[84:87], v[88:91], v[32:47]
	ds_read_b128 v[76:79], v127 offset:36864
	v_mfma_f32_32x32x16_bf16 v[0:15], v[84:87], v[92:95], v[0:15]
	ds_read_b128 v[68:71], v123 offset:36864
	s_waitcnt lgkmcnt(4)
	v_mfma_f32_32x32x16_bf16 v[48:63], v[96:99], v[104:107], v[48:63]
	v_mfma_f32_32x32x16_bf16 v[16:31], v[96:99], v[108:111], v[16:31]
	v_mfma_f32_32x32x16_bf16 v[32:47], v[100:103], v[104:107], v[32:47]
	v_mfma_f32_32x32x16_bf16 v[0:15], v[100:103], v[108:111], v[0:15]
	s_waitcnt lgkmcnt(0)
	v_mfma_f32_32x32x16_bf16 v[48:63], v[64:67], v[72:75], v[48:63]
	v_mfma_f32_32x32x16_bf16 v[16:31], v[64:67], v[76:79], v[16:31]
	v_mfma_f32_32x32x16_bf16 v[32:47], v[68:71], v[72:75], v[32:47]
	v_mfma_f32_32x32x16_bf16 v[0:15], v[68:71], v[76:79], v[0:15]
	s_barrier
	s_add_u32 m0, s98, 0x8000
	s_nop 0
	global_load_lds_dwordx4 v112, s[0:1] offset:0
	global_load_lds_dwordx4 v113, s[0:1] offset:1024
	global_load_lds_dwordx4 v114, s[0:1] offset:2048
	global_load_lds_dwordx4 v115, s[0:1] offset:3072
	s_add_u32 m0, s98, 0x9000
	s_nop 0
	global_load_lds_dwordx4 v116, s[0:1] offset:0
	global_load_lds_dwordx4 v117, s[0:1] offset:1024
	global_load_lds_dwordx4 v118, s[0:1] offset:2048
	global_load_lds_dwordx4 v119, s[0:1] offset:3072
	s_add_u32 s0, s0, 0x80
	s_addc_u32 s1, s1, 0
	s_sub_u32 s2, s2, 1
	s_waitcnt vmcnt(8)

.Lg2_first:
	s_barrier
	ds_read_b128 v[64:67], v120 offset:0
	ds_read_b128 v[72:75], v124 offset:0
	ds_read_b128 v[76:79], v124 offset:4096
	ds_read_b128 v[68:71], v120 offset:4096
	ds_read_b128 v[80:83], v121 offset:0
	ds_read_b128 v[88:91], v125 offset:0
	ds_read_b128 v[92:95], v125 offset:4096
	ds_read_b128 v[84:87], v121 offset:4096
	s_waitcnt lgkmcnt(4)
	v_mfma_f32_32x32x16_bf16 v[48:63], v[64:67], v[72:75], v[48:63]
	ds_read_b128 v[96:99], v122 offset:0
	v_mfma_f32_32x32x16_bf16 v[32:47], v[64:67], v[76:79], v[32:47]
	ds_read_b128 v[104:107], v126 offset:0
	v_mfma_f32_32x32x16_bf16 v[16:31], v[68:71], v[72:75], v[16:31]
	ds_read_b128 v[108:111], v126 offset:4096
	v_mfma_f32_32x32x16_bf16 v[0:15], v[68:71], v[76:79], v[0:15]
	ds_read_b128 v[100:103], v122 offset:4096
	s_waitcnt lgkmcnt(4)
	v_mfma_f32_32x32x16_bf16 v[48:63], v[80:83], v[88:91], v[48:63]
	ds_read_b128 v[64:67], v123 offset:0
	v_mfma_f32_32x32x16_bf16 v[32:47], v[80:83], v[92:95], v[32:47]
	ds_read_b128 v[72:75], v127 offset:0
	v_mfma_f32_32x32x16_bf16 v[16:31], v[84:87], v[88:91], v[16:31]
	ds_read_b128 v[76:79], v127 offset:4096
	v_mfma_f32_32x32x16_bf16 v[0:15], v[84:87], v[92:95], v[0:15]
	ds_read_b128 v[68:71], v123 offset:4096
	s_waitcnt lgkmcnt(4)
	v_mfma_f32_32x32x16_bf16 v[48:63], v[96:99], v[104:107], v[48:63]
	v_mfma_f32_32x32x16_bf16 v[32:47], v[96:99], v[108:111], v[32:47]
	v_mfma_f32_32x32x16_bf16 v[16:31], v[100:103], v[104:107], v[16:31]
	v_mfma_f32_32x32x16_bf16 v[0:15], v[100:103], v[108:111], v[0:15]
	s_waitcnt lgkmcnt(0)
	v_mfma_f32_32x32x16_bf16 v[48:63], v[64:67], v[72:75], v[48:63]
	v_mfma_f32_32x32x16_bf16 v[32:47], v[64:67], v[76:79], v[32:47]
	v_mfma_f32_32x32x16_bf16 v[16:31], v[68:71], v[72:75], v[16:31]
	v_mfma_f32_32x32x16_bf16 v[0:15], v[68:71], v[76:79], v[0:15]
	s_barrier
	s_add_u32 m0, s98, 0x0
	s_nop 0
	global_load_lds_dwordx4 v112, s[2:3] offset:0
	global_load_lds_dwordx4 v113, s[2:3] offset:1024
	global_load_lds_dwordx4 v114, s[2:3] offset:2048
	global_load_lds_dwordx4 v115, s[2:3] offset:3072
	s_add_u32 m0, s98, 0x1000
	s_nop 0
	global_load_lds_dwordx4 v116, s[2:3] offset:0
	global_load_lds_dwordx4 v117, s[2:3] offset:1024
	global_load_lds_dwordx4 v118, s[2:3] offset:2048
	global_load_lds_dwordx4 v119, s[2:3] offset:3072
	s_add_u32 s2, s2, 0x80
	s_addc_u32 s3, s3, 0
	s_cmp_lg_u32 s101, 0
	s_cbranch_scc1 .Lg2_w1p
	s_waitcnt vmcnt(8)
	s_branch .Lg2_s1

.Lg2_s1:
	s_barrier
	ds_read_b128 v[64:67], v120 offset:32768
	ds_read_b128 v[72:75], v124 offset:32768
	ds_read_b128 v[76:79], v124 offset:36864
	ds_read_b128 v[68:71], v120 offset:36864
	ds_read_b128 v[80:83], v121 offset:32768
	ds_read_b128 v[88:91], v125 offset:32768
	ds_read_b128 v[92:95], v125 offset:36864
	ds_read_b128 v[84:87], v121 offset:36864
	s_waitcnt lgkmcnt(4)
	v_mfma_f32_32x32x16_bf16 v[48:63], v[64:67], v[72:75], v[48:63]
	ds_read_b128 v[96:99], v122 offset:32768
	v_mfma_f32_32x32x16_bf16 v[32:47], v[64:67], v[76:79], v[32:47]
	ds_read_b128 v[104:107], v126 offset:32768
	v_mfma_f32_32x32x16_bf16 v[16:31], v[68:71], v[72:75], v[16:31]
	ds_read_b128 v[108:111], v126 offset:36864
	v_mfma_f32_32x32x16_bf16 v[0:15], v[68:71], v[76:79], v[0:15]
	ds_read_b128 v[100:103], v122 offset:36864
	s_waitcnt lgkmcnt(4)
	v_mfma_f32_32x32x16_bf16 v[48:63], v[80:83], v[88:91], v[48:63]
	ds_read_b128 v[64:67], v123 offset:32768
	v_mfma_f32_32x32x16_bf16 v[32:47], v[80:83], v[92:95], v[32:47]
	ds_read_b128 v[72:75], v127 offset:32768
	v_mfma_f32_32x32x16_bf16 v[16:31], v[84:87], v[88:91], v[16:31]
	ds_read_b128 v[76:79], v127 offset:36864
	v_mfma_f32_32x32x16_bf16 v[0:15], v[84:87], v[92:95], v[0:15]
	ds_read_b128 v[68:71], v123 offset:36864
	s_waitcnt lgkmcnt(4)
	v_mfma_f32_32x32x16_bf16 v[48:63], v[96:99], v[104:107], v[48:63]
	v_mfma_f32_32x32x16_bf16 v[32:47], v[96:99], v[108:111], v[32:47]
	v_mfma_f32_32x32x16_bf16 v[16:31], v[100:103], v[104:107], v[16:31]
	v_mfma_f32_32x32x16_bf16 v[0:15], v[100:103], v[108:111], v[0:15]
	s_waitcnt lgkmcnt(0)
	v_mfma_f32_32x32x16_bf16 v[48:63], v[64:67], v[72:75], v[48:63]
	v_mfma_f32_32x32x16_bf16 v[32:47], v[64:67], v[76:79], v[32:47]
	v_mfma_f32_32x32x16_bf16 v[16:31], v[68:71], v[72:75], v[16:31]
	v_mfma_f32_32x32x16_bf16 v[0:15], v[68:71], v[76:79], v[0:15]
	s_barrier
	s_add_u32 m0, s98, 0x8000
	s_nop 0
	global_load_lds_dwordx4 v112, s[2:3] offset:0
	global_load_lds_dwordx4 v113, s[2:3] offset:1024
	global_load_lds_dwordx4 v114, s[2:3] offset:2048
	global_load_lds_dwordx4 v115, s[2:3] offset:3072
	s_add_u32 m0, s98, 0x9000
	s_nop 0
	global_load_lds_dwordx4 v116, s[2:3] offset:0
	global_load_lds_dwordx4 v117, s[2:3] offset:1024
	global_load_lds_dwordx4 v118, s[2:3] offset:2048
	global_load_lds_dwordx4 v119, s[2:3] offset:3072
	s_add_u32 s2, s2, 0x80
	s_addc_u32 s3, s3, 0
	s_sub_u32 s6, s6, 1
	s_waitcnt vmcnt(8)

.Lg6_first:
	s_barrier
	ds_read_b128 v[64:67], v120 offset:0
	ds_read_b128 v[72:75], v124 offset:0
	ds_read_b128 v[76:79], v124 offset:4096
	ds_read_b128 v[68:71], v120 offset:4096
	ds_read_b128 v[80:83], v121 offset:0
	ds_read_b128 v[88:91], v125 offset:0
	ds_read_b128 v[92:95], v125 offset:4096
	ds_read_b128 v[84:87], v121 offset:4096
	s_waitcnt lgkmcnt(4)
	v_mfma_f32_32x32x16_bf16 v[48:63], v[64:67], v[72:75], v[48:63]
	ds_read_b128 v[96:99], v122 offset:0
	v_mfma_f32_32x32x16_bf16 v[32:47], v[64:67], v[76:79], v[32:47]
	ds_read_b128 v[104:107], v126 offset:0
	v_mfma_f32_32x32x16_bf16 v[16:31], v[68:71], v[72:75], v[16:31]
	ds_read_b128 v[108:111], v126 offset:4096
	v_mfma_f32_32x32x16_bf16 v[0:15], v[68:71], v[76:79], v[0:15]
	ds_read_b128 v[100:103], v122 offset:4096
	s_waitcnt lgkmcnt(4)
	v_mfma_f32_32x32x16_bf16 v[48:63], v[80:83], v[88:91], v[48:63]
	ds_read_b128 v[64:67], v123 offset:0
	v_mfma_f32_32x32x16_bf16 v[32:47], v[80:83], v[92:95], v[32:47]
	ds_read_b128 v[72:75], v127 offset:0
	v_mfma_f32_32x32x16_bf16 v[16:31], v[84:87], v[88:91], v[16:31]
	ds_read_b128 v[76:79], v127 offset:4096
	v_mfma_f32_32x32x16_bf16 v[0:15], v[84:87], v[92:95], v[0:15]
	ds_read_b128 v[68:71], v123 offset:4096
	s_waitcnt lgkmcnt(4)
	v_mfma_f32_32x32x16_bf16 v[48:63], v[96:99], v[104:107], v[48:63]
	v_mfma_f32_32x32x16_bf16 v[32:47], v[96:99], v[108:111], v[32:47]
	v_mfma_f32_32x32x16_bf16 v[16:31], v[100:103], v[104:107], v[16:31]
	v_mfma_f32_32x32x16_bf16 v[0:15], v[100:103], v[108:111], v[0:15]
	s_waitcnt lgkmcnt(0)
	v_mfma_f32_32x32x16_bf16 v[48:63], v[64:67], v[72:75], v[48:63]
	v_mfma_f32_32x32x16_bf16 v[32:47], v[64:67], v[76:79], v[32:47]
	v_mfma_f32_32x32x16_bf16 v[16:31], v[68:71], v[72:75], v[16:31]
	v_mfma_f32_32x32x16_bf16 v[0:15], v[68:71], v[76:79], v[0:15]
	s_barrier
	s_add_u32 m0, s98, 0x0
	s_nop 0
	global_load_lds_dwordx4 v112, s[4:5] offset:0
	global_load_lds_dwordx4 v113, s[4:5] offset:1024
	global_load_lds_dwordx4 v114, s[4:5] offset:2048
	global_load_lds_dwordx4 v115, s[4:5] offset:3072
	s_add_u32 m0, s98, 0x1000
	s_nop 0
	global_load_lds_dwordx4 v116, s[4:5] offset:0
	global_load_lds_dwordx4 v117, s[4:5] offset:1024
	global_load_lds_dwordx4 v118, s[4:5] offset:2048
	global_load_lds_dwordx4 v119, s[4:5] offset:3072
	s_add_u32 s4, s4, 0x80
	s_addc_u32 s5, s5, 0
	s_cmp_lg_u32 s101, 0
	s_cbranch_scc1 .Lg6_w1p
	s_waitcnt vmcnt(8)
	s_branch .Lg6_s1

.Lg6_s1:
	s_barrier
	ds_read_b128 v[64:67], v120 offset:32768
	ds_read_b128 v[72:75], v124 offset:32768
	ds_read_b128 v[76:79], v124 offset:36864
	ds_read_b128 v[68:71], v120 offset:36864
	ds_read_b128 v[80:83], v121 offset:32768
	ds_read_b128 v[88:91], v125 offset:32768
	ds_read_b128 v[92:95], v125 offset:36864
	ds_read_b128 v[84:87], v121 offset:36864
	s_waitcnt lgkmcnt(4)
	v_mfma_f32_32x32x16_bf16 v[48:63], v[64:67], v[72:75], v[48:63]
	ds_read_b128 v[96:99], v122 offset:32768
	v_mfma_f32_32x32x16_bf16 v[32:47], v[64:67], v[76:79], v[32:47]
	ds_read_b128 v[104:107], v126 offset:32768
	v_mfma_f32_32x32x16_bf16 v[16:31], v[68:71], v[72:75], v[16:31]
	ds_read_b128 v[108:111], v126 offset:36864
	v_mfma_f32_32x32x16_bf16 v[0:15], v[68:71], v[76:79], v[0:15]
	ds_read_b128 v[100:103], v122 offset:36864
	s_waitcnt lgkmcnt(4)
	v_mfma_f32_32x32x16_bf16 v[48:63], v[80:83], v[88:91], v[48:63]
	ds_read_b128 v[64:67], v123 offset:32768
	v_mfma_f32_32x32x16_bf16 v[32:47], v[80:83], v[92:95], v[32:47]
	ds_read_b128 v[72:75], v127 offset:32768
	v_mfma_f32_32x32x16_bf16 v[16:31], v[84:87], v[88:91], v[16:31]
	ds_read_b128 v[76:79], v127 offset:36864
	v_mfma_f32_32x32x16_bf16 v[0:15], v[84:87], v[92:95], v[0:15]
	ds_read_b128 v[68:71], v123 offset:36864
	s_waitcnt lgkmcnt(4)
	v_mfma_f32_32x32x16_bf16 v[48:63], v[96:99], v[104:107], v[48:63]
	v_mfma_f32_32x32x16_bf16 v[32:47], v[96:99], v[108:111], v[32:47]
	v_mfma_f32_32x32x16_bf16 v[16:31], v[100:103], v[104:107], v[16:31]
	v_mfma_f32_32x32x16_bf16 v[0:15], v[100:103], v[108:111], v[0:15]
	s_waitcnt lgkmcnt(0)
	v_mfma_f32_32x32x16_bf16 v[48:63], v[64:67], v[72:75], v[48:63]
	v_mfma_f32_32x32x16_bf16 v[32:47], v[64:67], v[76:79], v[32:47]
	v_mfma_f32_32x32x16_bf16 v[16:31], v[68:71], v[72:75], v[16:31]
	v_mfma_f32_32x32x16_bf16 v[0:15], v[68:71], v[76:79], v[0:15]
	s_barrier
	s_add_u32 m0, s98, 0x8000
	s_nop 0
	global_load_lds_dwordx4 v112, s[4:5] offset:0
	global_load_lds_dwordx4 v113, s[4:5] offset:1024
	global_load_lds_dwordx4 v114, s[4:5] offset:2048
	global_load_lds_dwordx4 v115, s[4:5] offset:3072
	s_add_u32 m0, s98, 0x9000
	s_nop 0
	global_load_lds_dwordx4 v116, s[4:5] offset:0
	global_load_lds_dwordx4 v117, s[4:5] offset:1024
	global_load_lds_dwordx4 v118, s[4:5] offset:2048
	global_load_lds_dwordx4 v119, s[4:5] offset:3072
	s_add_u32 s4, s4, 0x80
	s_addc_u32 s5, s5, 0
	s_sub_u32 s6, s6, 1
	s_waitcnt vmcnt(8)
